# P0 rmsnorm(x) to bf16: gain loads hoisted out of the row loop, four row pairs of a wave in flight with counted vmcnt
# baseline (speedup 1.0000x reference)
; #define GAS __attribute__((address_space(1)))
; __device__ __forceinline__ unsigned pk2(float lo, float hi) { const f32x2_t_ v = {lo, hi}; return __builtin_bit_cast(unsigned, __builtin_convertvector(v, bf16x2_t_)); }
; __device__ __forceinline__ const float* kin(int k) { KArgs p = (KArgs)__builtin_amdgcn_kernarg_segment_ptr(); asm volatile("" : "+s"(p)); return p->in[k]; }
; __device__ __forceinline__ void rms_row2_bf16(const float* xrowA, const float* xrowB, const float* g, bf16* orowA, bf16* orowB, int lane) {
;     const int hl = lane & 31, hw = lane >> 5;
;     const GAS f32x4* xr = (const GAS f32x4*)(hw ? xrowB : xrowA) + hl; const GAS f32x4* gr = (const GAS f32x4*)g + hl;
;     f32x4 v[8]; float s = 0.f;
; #pragma unroll
;     for (int j = 0; j < 8; ++j) { v[j] = xr[32 * j]; s += (v[j].x * v[j].x + v[j].y * v[j].y) + (v[j].z * v[j].z + v[j].w * v[j].w); }
; #pragma unroll
;     for (int o = 1; o < 32; o <<= 1) s += __shfl_xor(s, o);
;     const float rstd = 1.f / sqrtf(s * (1.f / DM) + EPS);
;     GAS v2u* o8 = (GAS v2u*)(hw ? orowB : orowA) + hl;
; #pragma unroll
;     for (int j = 0; j < 8; ++j) { const f32x4 gg = gr[32 * j]; v2u w; w.x = pk2(v[j].x * rstd * gg.x, v[j].y * rstd * gg.y); w.y = pk2(v[j].z * rstd * gg.z, v[j].w * rstd * gg.w); o8[32 * j] = w; }
; }
; __global__ void __launch_bounds__(NWAVES * 64, 2) mk_fwd(Args args) {
;     ...
;         { const float* xp = kin(0); const float* xs = kin(1); const float* g1 = kin(5);
;           for (int m = 2 * GW_; m < T; m += 2 * NGW) { const float* ra = m < TP ? xp + (size_t)m * DM : xs + (size_t)(m - TP) * DM;
;               rms_row2_bf16(ra, ra + DM, g1, XN + (size_t)m * DM, XN + (size_t)(m + 1) * DM, F.lane); } }
.LBB0_49:
	s_lshl_b32 s3, s33, 4
	s_waitcnt lgkmcnt(0)
	s_lshl_b32 s8, s50, 1
	s_add_i32 s3, s3, s8
	s_mov_b64 s[6:7], s[0:1]
	s_mov_b64 s[12:13], s[0:1]
	s_mov_b64 s[14:15], s[0:1]
	s_cmpk_gt_i32 s3, 0x43ff
	s_cbranch_scc1 .LBB0_52
	v_mov_b32_e32 v1, 0x1000
	v_cmp_lt_u32_e32 vcc, 31, v189
	s_load_dwordx2 s[8:9], s[6:7], 0x0
	s_load_dwordx2 s[10:11], s[12:13], 0x8
	s_load_dwordx2 s[16:17], s[14:15], 0x28
	v_cndmask_b32_e32 v4, 0, v1, vcc
	v_mbcnt_lo_u32_b32 v1, -1, 0
	v_mbcnt_hi_u32_b32 v3, -1, v1
	v_and_b32_e32 v1, 64, v3
	v_add_u32_e32 v6, 64, v1
	v_xor_b32_e32 v1, 1, v3
	v_cmp_lt_i32_e64 s[6:7], v1, v6
	v_xor_b32_e32 v7, 2, v3
	v_mov_b32_e32 v5, 0
	v_cndmask_b32_e64 v1, v3, v1, s[6:7]
	v_cmp_lt_i32_e64 s[6:7], v7, v6
	v_lshlrev_b32_e32 v8, 3, v2
	v_mov_b32_e32 v9, v5
	v_cndmask_b32_e64 v7, v3, v7, s[6:7]
	v_lshlrev_b32_e32 v12, 2, v7
	v_xor_b32_e32 v7, 4, v3
	v_cmp_lt_i32_e64 s[6:7], v7, v6
	s_lshl_b32 s14, s18, 4
	v_lshlrev_b32_e32 v1, 2, v1
	v_cndmask_b32_e64 v7, v3, v7, s[6:7]
	v_lshlrev_b32_e32 v13, 2, v7
	v_xor_b32_e32 v7, 8, v3
	v_cmp_lt_i32_e64 s[6:7], v7, v6
	v_cndmask_b32_e64 v16, 0, 1, vcc
	v_lshl_add_u64 v[8:9], s[30:31], 0, v[8:9]
	v_cndmask_b32_e64 v7, v3, v7, s[6:7]
	v_lshlrev_b32_e32 v14, 2, v7
	v_xor_b32_e32 v7, 16, v3
	v_cmp_lt_i32_e64 s[6:7], v7, v6
	v_lshlrev_b32_e32 v6, 4, v2
	s_ashr_i32 s15, s3, 31
	v_cndmask_b32_e64 v3, v3, v7, s[6:7]
	v_mov_b32_e32 v7, v5
	v_lshlrev_b32_e32 v15, 2, v3
	s_waitcnt lgkmcnt(0)
	v_lshl_add_u64 v[6:7], s[16:17], 0, v[6:7]
	s_ashr_i32 s16, s14, 31
	s_mov_b64 s[12:13], 0
	v_lshlrev_b32_e32 v2, 4, v2
	v_mov_b32_e32 v3, v5
	v_mov_b32_e32 v17, 0x358637bd
	s_mov_b32 s17, 0xf800000
	v_mov_b32_e32 v18, 0x260
	s_mov_b32 s19, s3
	global_load_dwordx4 v[88:91], v[6:7], off
	global_load_dwordx4 v[92:95], v[6:7], off offset:512
	global_load_dwordx4 v[96:99], v[6:7], off offset:1024
	global_load_dwordx4 v[100:103], v[6:7], off offset:1536
	global_load_dwordx4 v[104:107], v[6:7], off offset:2048
	global_load_dwordx4 v[108:111], v[6:7], off offset:2560
	global_load_dwordx4 v[112:115], v[6:7], off offset:3072
	global_load_dwordx4 v[116:119], v[6:7], off offset:3584
.Lp0r_outer:
	s_mov_b32 s34, 0
	s_add_i32 s6, s19, 0xffffc000
	s_add_u32 s28, s3, s12
	s_addc_u32 s7, s15, s13
	s_cmpk_lt_i32 s19, 0x4000
	s_cselect_b32 s7, s7, 0
	s_cselect_b32 s6, s28, s6
	s_cselect_b32 s28, s9, s11
	s_cselect_b32 s29, s8, s10
	s_lshl_b64 s[6:7], s[6:7], 12
	s_add_u32 s6, s29, s6
	s_addc_u32 s7, s28, s7
	v_lshl_add_u64 v[234:235], s[6:7], 0, v[4:5]
	v_lshl_add_u64 v[234:235], v[234:235], 0, v[2:3]
	global_load_dwordx4 v[24:27], v[234:235], off
	global_load_dwordx4 v[28:31], v[234:235], off offset:512
	global_load_dwordx4 v[32:35], v[234:235], off offset:1024
	global_load_dwordx4 v[36:39], v[234:235], off offset:1536
	global_load_dwordx4 v[40:43], v[234:235], off offset:2048
	global_load_dwordx4 v[44:47], v[234:235], off offset:2560
	global_load_dwordx4 v[48:51], v[234:235], off offset:3072
	global_load_dwordx4 v[52:55], v[234:235], off offset:3584
	v_add_u32_e32 v226, s19, v16
	v_ashrrev_i32_e32 v227, 31, v226
	v_lshlrev_b64 v[226:227], 11, v[226:227]
	v_lshl_add_u64 v[226:227], v[8:9], 0, v[226:227]
	s_add_i32 s19, s19, s14
	s_add_u32 s12, s12, s14
	s_addc_u32 s13, s13, s16
	s_add_i32 s34, s34, 1
	s_cmpk_gt_i32 s19, 0x43ff
	s_cbranch_scc1 .Lp0r_issued
	s_add_i32 s6, s19, 0xffffc000
	s_add_u32 s28, s3, s12
	s_addc_u32 s7, s15, s13
	s_cmpk_lt_i32 s19, 0x4000
	s_cselect_b32 s7, s7, 0
	s_cselect_b32 s6, s28, s6
	s_cselect_b32 s28, s9, s11
	s_cselect_b32 s29, s8, s10
	s_lshl_b64 s[6:7], s[6:7], 12
	s_add_u32 s6, s29, s6
	s_addc_u32 s7, s28, s7
	v_lshl_add_u64 v[234:235], s[6:7], 0, v[4:5]
	v_lshl_add_u64 v[234:235], v[234:235], 0, v[2:3]
	global_load_dwordx4 v[56:59], v[234:235], off
	global_load_dwordx4 v[60:63], v[234:235], off offset:512
	global_load_dwordx4 v[64:67], v[234:235], off offset:1024
	global_load_dwordx4 v[68:71], v[234:235], off offset:1536
	global_load_dwordx4 v[72:75], v[234:235], off offset:2048
	global_load_dwordx4 v[76:79], v[234:235], off offset:2560
	global_load_dwordx4 v[80:83], v[234:235], off offset:3072
	global_load_dwordx4 v[84:87], v[234:235], off offset:3584
	v_add_u32_e32 v228, s19, v16
	v_ashrrev_i32_e32 v229, 31, v228
	v_lshlrev_b64 v[228:229], 11, v[228:229]
	v_lshl_add_u64 v[228:229], v[8:9], 0, v[228:229]
	s_add_i32 s19, s19, s14
	s_add_u32 s12, s12, s14
	s_addc_u32 s13, s13, s16
	s_add_i32 s34, s34, 1
	s_cmpk_gt_i32 s19, 0x43ff
	s_cbranch_scc1 .Lp0r_issued
	s_add_i32 s6, s19, 0xffffc000
	s_add_u32 s28, s3, s12
	s_addc_u32 s7, s15, s13
	s_cmpk_lt_i32 s19, 0x4000
	s_cselect_b32 s7, s7, 0
	s_cselect_b32 s6, s28, s6
	s_cselect_b32 s28, s9, s11
	s_cselect_b32 s29, s8, s10
	s_lshl_b64 s[6:7], s[6:7], 12
	s_add_u32 s6, s29, s6
	s_addc_u32 s7, s28, s7
	v_lshl_add_u64 v[234:235], s[6:7], 0, v[4:5]
	v_lshl_add_u64 v[234:235], v[234:235], 0, v[2:3]
	global_load_dwordx4 v[120:123], v[234:235], off
	global_load_dwordx4 v[124:127], v[234:235], off offset:512
	global_load_dwordx4 v[128:131], v[234:235], off offset:1024
	global_load_dwordx4 v[132:135], v[234:235], off offset:1536
	global_load_dwordx4 v[136:139], v[234:235], off offset:2048
	global_load_dwordx4 v[140:143], v[234:235], off offset:2560
	global_load_dwordx4 v[144:147], v[234:235], off offset:3072
	global_load_dwordx4 v[148:151], v[234:235], off offset:3584
	v_add_u32_e32 v230, s19, v16
	v_ashrrev_i32_e32 v231, 31, v230
	v_lshlrev_b64 v[230:231], 11, v[230:231]
	v_lshl_add_u64 v[230:231], v[8:9], 0, v[230:231]
	s_add_i32 s19, s19, s14
	s_add_u32 s12, s12, s14
	s_addc_u32 s13, s13, s16
	s_add_i32 s34, s34, 1
	s_cmpk_gt_i32 s19, 0x43ff
	s_cbranch_scc1 .Lp0r_issued
	s_add_i32 s6, s19, 0xffffc000
	s_add_u32 s28, s3, s12
	s_addc_u32 s7, s15, s13
	s_cmpk_lt_i32 s19, 0x4000
	s_cselect_b32 s7, s7, 0
	s_cselect_b32 s6, s28, s6
	s_cselect_b32 s28, s9, s11
	s_cselect_b32 s29, s8, s10
	s_lshl_b64 s[6:7], s[6:7], 12
	s_add_u32 s6, s29, s6
	s_addc_u32 s7, s28, s7
	v_lshl_add_u64 v[234:235], s[6:7], 0, v[4:5]
	v_lshl_add_u64 v[234:235], v[234:235], 0, v[2:3]
	global_load_dwordx4 v[152:155], v[234:235], off
	global_load_dwordx4 v[156:159], v[234:235], off offset:512
	global_load_dwordx4 v[160:163], v[234:235], off offset:1024
	global_load_dwordx4 v[164:167], v[234:235], off offset:1536
	global_load_dwordx4 v[168:171], v[234:235], off offset:2048
	global_load_dwordx4 v[172:175], v[234:235], off offset:2560
	global_load_dwordx4 v[176:179], v[234:235], off offset:3072
	global_load_dwordx4 v[180:183], v[234:235], off offset:3584
	v_add_u32_e32 v232, s19, v16
	v_ashrrev_i32_e32 v233, 31, v232
	v_lshlrev_b64 v[232:233], 11, v[232:233]
	v_lshl_add_u64 v[232:233], v[8:9], 0, v[232:233]
	s_add_i32 s19, s19, s14
	s_add_u32 s12, s12, s14
	s_addc_u32 s13, s13, s16
	s_add_i32 s34, s34, 1
; #define GAS __attribute__((address_space(1)))
; __device__ __forceinline__ unsigned pk2(float lo, float hi) { const f32x2_t_ v = {lo, hi}; return __builtin_bit_cast(unsigned, __builtin_convertvector(v, bf16x2_t_)); }
; __device__ __forceinline__ void rms_row2_bf16(const float* xrowA, const float* xrowB, const float* g, bf16* orowA, bf16* orowB, int lane) {
;     const int hl = lane & 31, hw = lane >> 5;
;     const GAS f32x4* xr = (const GAS f32x4*)(hw ? xrowB : xrowA) + hl; const GAS f32x4* gr = (const GAS f32x4*)g + hl;
;     f32x4 v[8]; float s = 0.f;
; #pragma unroll
;     for (int j = 0; j < 8; ++j) { v[j] = xr[32 * j]; s += (v[j].x * v[j].x + v[j].y * v[j].y) + (v[j].z * v[j].z + v[j].w * v[j].w); }
; #pragma unroll
;     for (int o = 1; o < 32; o <<= 1) s += __shfl_xor(s, o);
;     const float rstd = 1.f / sqrtf(s * (1.f / DM) + EPS);
;     GAS v2u* o8 = (GAS v2u*)(hw ? orowB : orowA) + hl;
; #pragma unroll
;     for (int j = 0; j < 8; ++j) { const f32x4 gg = gr[32 * j]; v2u w; w.x = pk2(v[j].x * rstd * gg.x, v[j].y * rstd * gg.y); w.y = pk2(v[j].z * rstd * gg.z, v[j].w * rstd * gg.w); o8[32 * j] = w; }
; }
.Lp0r_issued:
	s_cmp_lt_u32 s34, 4
	s_cbranch_scc0 .Lp0r_go
	s_waitcnt vmcnt(0)
.Lp0r_go:
	s_waitcnt vmcnt(24)
	v_mov_b32_e32 v194, v25
	v_mov_b32_e32 v195, v29
	v_pk_mul_f32 v[196:197], v[34:35], v[34:35]
	v_pk_mul_f32 v[198:199], v[32:33], v[32:33]
	v_pk_mul_f32 v[200:201], v[46:47], v[46:47]
	v_pk_mul_f32 v[202:203], v[44:45], v[44:45]
	v_mov_b32_e32 v206, v27
	v_mov_b32_e32 v207, v31
	v_mov_b32_e32 v192, v24
	v_mov_b32_e32 v193, v28
	v_mov_b32_e32 v204, v26
	v_mov_b32_e32 v205, v30
	v_pk_mov_b32 v[216:217], v[198:199], v[196:197] op_sel:[1,0]
	v_mov_b32_e32 v199, v197
	v_pk_mov_b32 v[196:197], v[202:203], v[200:201] op_sel:[1,0]
	v_mov_b32_e32 v203, v201
	v_pk_mul_f32 v[194:195], v[194:195], v[194:195]
	v_pk_mul_f32 v[200:201], v[206:207], v[206:207]
	v_pk_fma_f32 v[192:193], v[192:193], v[192:193], v[194:195]
	v_pk_fma_f32 v[194:195], v[204:205], v[204:205], v[200:201]
	v_mul_f32_e32 v208, v37, v37
	v_mul_f32_e32 v210, v39, v39
	v_pk_add_f32 v[198:199], v[216:217], v[198:199]
	v_pk_add_f32 v[192:193], v[192:193], v[194:195]
	v_mul_f32_e32 v224, v40, v40
	v_mul_f32_e32 v215, v42, v42
	v_mul_f32_e32 v218, v43, v43
	v_mul_f32_e32 v221, v41, v41
	v_pk_fma_f32 v[206:207], v[36:37], v[36:37], v[208:209] op_sel_hi:[1,1,0]
	v_pk_fma_f32 v[208:209], v[38:39], v[38:39], v[210:211] op_sel_hi:[1,1,0]
	v_pk_add_f32 v[198:199], v[198:199], v[198:199] op_sel:[0,1] op_sel_hi:[1,0]
	v_pk_add_f32 v[192:193], v[192:193], v[192:193] op_sel:[0,1] op_sel_hi:[1,0]
	v_mov_b32_e32 v207, v215
	v_mov_b32_e32 v209, v218
	v_mov_b32_e32 v199, v221
	v_mov_b32_e32 v193, v224
	v_pk_add_f32 v[194:195], v[206:207], v[208:209]
	v_pk_add_f32 v[192:193], v[192:193], v[198:199]
	v_mul_f32_e32 v212, v49, v49
	v_mul_f32_e32 v214, v51, v51
	v_pk_add_f32 v[196:197], v[196:197], v[202:203]
	v_pk_add_f32 v[192:193], v[192:193], v[194:195]
	v_mul_f32_e32 v219, v54, v54
	v_mul_f32_e32 v220, v55, v55
	v_mul_f32_e32 v222, v52, v52
	v_mul_f32_e32 v223, v53, v53
	v_pk_fma_f32 v[210:211], v[48:49], v[48:49], v[212:213] op_sel_hi:[1,1,0]
	v_pk_fma_f32 v[212:213], v[50:51], v[50:51], v[214:215] op_sel_hi:[1,1,0]
	v_pk_add_f32 v[196:197], v[196:197], v[196:197] op_sel:[0,1] op_sel_hi:[1,0]
	v_pk_add_f32 v[192:193], v[192:193], v[192:193] op_sel:[0,1] op_sel_hi:[1,0]
	v_mov_b32_e32 v211, v219
	v_mov_b32_e32 v213, v220
	v_mov_b32_e32 v197, v223
	v_mov_b32_e32 v193, v222
	v_pk_add_f32 v[200:201], v[210:211], v[212:213]
	v_pk_add_f32 v[192:193], v[192:193], v[196:197]
	s_nop 0
	v_pk_add_f32 v[192:193], v[192:193], v[200:201]
	s_nop 0
	v_add_f32_e32 v224, v192, v193
	ds_bpermute_b32 v192, v1, v224
	s_waitcnt lgkmcnt(0)
	v_add_f32_e32 v224, v224, v192
	ds_bpermute_b32 v192, v12, v224
	s_waitcnt lgkmcnt(0)
	v_add_f32_e32 v224, v224, v192
	ds_bpermute_b32 v192, v13, v224
	s_waitcnt lgkmcnt(0)
	v_add_f32_e32 v224, v224, v192
	ds_bpermute_b32 v192, v14, v224
	s_waitcnt lgkmcnt(0)
	v_add_f32_e32 v224, v224, v192
	ds_bpermute_b32 v192, v15, v224
	s_waitcnt lgkmcnt(0)
	v_add_f32_e32 v224, v224, v192
	v_fmamk_f32 v224, v224, 0x3a800000, v17
	v_mul_f32_e32 v192, 0x4f800000, v224
	v_cmp_gt_f32_e32 vcc, s17, v224
	s_nop 1
	v_cndmask_b32_e32 v224, v224, v192, vcc
	v_sqrt_f32_e32 v192, v224
	s_nop 0
	v_add_u32_e32 v193, -1, v192
	v_add_u32_e32 v194, 1, v192
	v_fma_f32 v195, -v193, v192, v224
	v_fma_f32 v196, -v194, v192, v224
	v_cmp_ge_f32_e64 s[6:7], 0, v195
	s_nop 1
	v_cndmask_b32_e64 v192, v192, v193, s[6:7]
	v_cmp_lt_f32_e64 s[6:7], 0, v196
	s_nop 1
	v_cndmask_b32_e64 v192, v192, v194, s[6:7]
	v_mul_f32_e32 v193, 0x37800000, v192
	v_cndmask_b32_e32 v192, v192, v193, vcc
	v_cmp_class_f32_e32 vcc, v224, v18
	s_nop 1
	v_cndmask_b32_e32 v224, v192, v224, vcc
	v_div_scale_f32 v192, s[6:7], v224, v224, 1.0
	v_rcp_f32_e32 v194, v192
	v_div_scale_f32 v193, vcc, 1.0, v224, 1.0
	v_fma_f32 v195, -v192, v194, 1.0
	v_fmac_f32_e32 v194, v195, v194
	v_mul_f32_e32 v195, v193, v194
	v_fma_f32 v196, -v192, v195, v193
	v_fmac_f32_e32 v195, v196, v194
	v_fma_f32 v192, -v192, v195, v193
	v_div_fmas_f32 v192, v192, v194, v195
	v_div_fixup_f32 v192, v192, v224, 1.0
	v_pk_mul_f32 v[24:25], v[24:25], v[192:193] op_sel_hi:[1,0]
	v_pk_mul_f32 v[26:27], v[26:27], v[192:193] op_sel_hi:[1,0]
	v_pk_mul_f32 v[24:25], v[88:89], v[24:25]
	v_pk_mul_f32 v[26:27], v[90:91], v[26:27]
	v_cvt_pk_bf16_f32 v24, v24, v25
	v_cvt_pk_bf16_f32 v25, v26, v27
	global_store_dwordx2 v[226:227], v[24:25], off
	v_pk_mul_f32 v[28:29], v[28:29], v[192:193] op_sel_hi:[1,0]
	v_pk_mul_f32 v[30:31], v[30:31], v[192:193] op_sel_hi:[1,0]
	v_pk_mul_f32 v[28:29], v[92:93], v[28:29]
	v_pk_mul_f32 v[30:31], v[94:95], v[30:31]
	v_cvt_pk_bf16_f32 v28, v28, v29
	v_cvt_pk_bf16_f32 v29, v30, v31
	global_store_dwordx2 v[226:227], v[28:29], off offset:256
	v_pk_mul_f32 v[32:33], v[32:33], v[192:193] op_sel_hi:[1,0]
	v_pk_mul_f32 v[34:35], v[34:35], v[192:193] op_sel_hi:[1,0]
	v_pk_mul_f32 v[32:33], v[96:97], v[32:33]
	v_pk_mul_f32 v[34:35], v[98:99], v[34:35]
	v_cvt_pk_bf16_f32 v32, v32, v33
	v_cvt_pk_bf16_f32 v33, v34, v35
	global_store_dwordx2 v[226:227], v[32:33], off offset:512
	v_pk_mul_f32 v[36:37], v[36:37], v[192:193] op_sel_hi:[1,0]
	v_pk_mul_f32 v[38:39], v[38:39], v[192:193] op_sel_hi:[1,0]
	v_pk_mul_f32 v[36:37], v[100:101], v[36:37]
	v_pk_mul_f32 v[38:39], v[102:103], v[38:39]
	v_cvt_pk_bf16_f32 v36, v36, v37
	v_cvt_pk_bf16_f32 v37, v38, v39
	global_store_dwordx2 v[226:227], v[36:37], off offset:768
	v_pk_mul_f32 v[40:41], v[40:41], v[192:193] op_sel_hi:[1,0]
	v_pk_mul_f32 v[42:43], v[42:43], v[192:193] op_sel_hi:[1,0]
	v_pk_mul_f32 v[40:41], v[104:105], v[40:41]
	v_pk_mul_f32 v[42:43], v[106:107], v[42:43]
	v_cvt_pk_bf16_f32 v40, v40, v41
	v_cvt_pk_bf16_f32 v41, v42, v43
	global_store_dwordx2 v[226:227], v[40:41], off offset:1024
	v_pk_mul_f32 v[44:45], v[44:45], v[192:193] op_sel_hi:[1,0]
	v_pk_mul_f32 v[46:47], v[46:47], v[192:193] op_sel_hi:[1,0]
	v_pk_mul_f32 v[44:45], v[108:109], v[44:45]
	v_pk_mul_f32 v[46:47], v[110:111], v[46:47]
	v_cvt_pk_bf16_f32 v44, v44, v45
	v_cvt_pk_bf16_f32 v45, v46, v47
	global_store_dwordx2 v[226:227], v[44:45], off offset:1280
	v_pk_mul_f32 v[48:49], v[48:49], v[192:193] op_sel_hi:[1,0]
	v_pk_mul_f32 v[50:51], v[50:51], v[192:193] op_sel_hi:[1,0]
	v_pk_mul_f32 v[48:49], v[112:113], v[48:49]
	v_pk_mul_f32 v[50:51], v[114:115], v[50:51]
	v_cvt_pk_bf16_f32 v48, v48, v49
	v_cvt_pk_bf16_f32 v49, v50, v51
	global_store_dwordx2 v[226:227], v[48:49], off offset:1536
	v_pk_mul_f32 v[52:53], v[52:53], v[192:193] op_sel_hi:[1,0]
	v_pk_mul_f32 v[54:55], v[54:55], v[192:193] op_sel_hi:[1,0]
	v_pk_mul_f32 v[52:53], v[116:117], v[52:53]
	v_pk_mul_f32 v[54:55], v[118:119], v[54:55]
	v_cvt_pk_bf16_f32 v52, v52, v53
	v_cvt_pk_bf16_f32 v53, v54, v55
	global_store_dwordx2 v[226:227], v[52:53], off offset:1792
	s_cmp_lt_u32 1, s34
	s_cbranch_scc0 .Lp0r_done
; #define GAS __attribute__((address_space(1)))
; __device__ __forceinline__ unsigned pk2(float lo, float hi) { const f32x2_t_ v = {lo, hi}; return __builtin_bit_cast(unsigned, __builtin_convertvector(v, bf16x2_t_)); }
; __device__ __forceinline__ void rms_row2_bf16(const float* xrowA, const float* xrowB, const float* g, bf16* orowA, bf16* orowB, int lane) {
;     const int hl = lane & 31, hw = lane >> 5;
;     const GAS f32x4* xr = (const GAS f32x4*)(hw ? xrowB : xrowA) + hl; const GAS f32x4* gr = (const GAS f32x4*)g + hl;
;     f32x4 v[8]; float s = 0.f;
; #pragma unroll
;     for (int j = 0; j < 8; ++j) { v[j] = xr[32 * j]; s += (v[j].x * v[j].x + v[j].y * v[j].y) + (v[j].z * v[j].z + v[j].w * v[j].w); }
; #pragma unroll
;     for (int o = 1; o < 32; o <<= 1) s += __shfl_xor(s, o);
;     const float rstd = 1.f / sqrtf(s * (1.f / DM) + EPS);
;     GAS v2u* o8 = (GAS v2u*)(hw ? orowB : orowA) + hl;
; #pragma unroll
;     for (int j = 0; j < 8; ++j) { const f32x4 gg = gr[32 * j]; v2u w; w.x = pk2(v[j].x * rstd * gg.x, v[j].y * rstd * gg.y); w.y = pk2(v[j].z * rstd * gg.z, v[j].w * rstd * gg.w); o8[32 * j] = w; }
; }
	s_waitcnt vmcnt(24)
	v_mov_b32_e32 v194, v57
	v_mov_b32_e32 v195, v61
	v_pk_mul_f32 v[196:197], v[66:67], v[66:67]
	v_pk_mul_f32 v[198:199], v[64:65], v[64:65]
	v_pk_mul_f32 v[200:201], v[78:79], v[78:79]
	v_pk_mul_f32 v[202:203], v[76:77], v[76:77]
	v_mov_b32_e32 v206, v59
	v_mov_b32_e32 v207, v63
	v_mov_b32_e32 v192, v56
	v_mov_b32_e32 v193, v60
	v_mov_b32_e32 v204, v58
	v_mov_b32_e32 v205, v62
	v_pk_mov_b32 v[216:217], v[198:199], v[196:197] op_sel:[1,0]
	v_mov_b32_e32 v199, v197
	v_pk_mov_b32 v[196:197], v[202:203], v[200:201] op_sel:[1,0]
	v_mov_b32_e32 v203, v201
	v_pk_mul_f32 v[194:195], v[194:195], v[194:195]
	v_pk_mul_f32 v[200:201], v[206:207], v[206:207]
	v_pk_fma_f32 v[192:193], v[192:193], v[192:193], v[194:195]
	v_pk_fma_f32 v[194:195], v[204:205], v[204:205], v[200:201]
	v_mul_f32_e32 v208, v69, v69
	v_mul_f32_e32 v210, v71, v71
	v_pk_add_f32 v[198:199], v[216:217], v[198:199]
	v_pk_add_f32 v[192:193], v[192:193], v[194:195]
	v_mul_f32_e32 v224, v72, v72
	v_mul_f32_e32 v215, v74, v74
	v_mul_f32_e32 v218, v75, v75
	v_mul_f32_e32 v221, v73, v73
	v_pk_fma_f32 v[206:207], v[68:69], v[68:69], v[208:209] op_sel_hi:[1,1,0]
	v_pk_fma_f32 v[208:209], v[70:71], v[70:71], v[210:211] op_sel_hi:[1,1,0]
	v_pk_add_f32 v[198:199], v[198:199], v[198:199] op_sel:[0,1] op_sel_hi:[1,0]
	v_pk_add_f32 v[192:193], v[192:193], v[192:193] op_sel:[0,1] op_sel_hi:[1,0]
	v_mov_b32_e32 v207, v215
	v_mov_b32_e32 v209, v218
	v_mov_b32_e32 v199, v221
	v_mov_b32_e32 v193, v224
	v_pk_add_f32 v[194:195], v[206:207], v[208:209]
	v_pk_add_f32 v[192:193], v[192:193], v[198:199]
	v_mul_f32_e32 v212, v81, v81
	v_mul_f32_e32 v214, v83, v83
	v_pk_add_f32 v[196:197], v[196:197], v[202:203]
	v_pk_add_f32 v[192:193], v[192:193], v[194:195]
	v_mul_f32_e32 v219, v86, v86
	v_mul_f32_e32 v220, v87, v87
	v_mul_f32_e32 v222, v84, v84
	v_mul_f32_e32 v223, v85, v85
	v_pk_fma_f32 v[210:211], v[80:81], v[80:81], v[212:213] op_sel_hi:[1,1,0]
	v_pk_fma_f32 v[212:213], v[82:83], v[82:83], v[214:215] op_sel_hi:[1,1,0]
	v_pk_add_f32 v[196:197], v[196:197], v[196:197] op_sel:[0,1] op_sel_hi:[1,0]
	v_pk_add_f32 v[192:193], v[192:193], v[192:193] op_sel:[0,1] op_sel_hi:[1,0]
	v_mov_b32_e32 v211, v219
	v_mov_b32_e32 v213, v220
	v_mov_b32_e32 v197, v223
	v_mov_b32_e32 v193, v222
	v_pk_add_f32 v[200:201], v[210:211], v[212:213]
	v_pk_add_f32 v[192:193], v[192:193], v[196:197]
	s_nop 0
	v_pk_add_f32 v[192:193], v[192:193], v[200:201]
	s_nop 0
	v_add_f32_e32 v224, v192, v193
	ds_bpermute_b32 v192, v1, v224
	s_waitcnt lgkmcnt(0)
	v_add_f32_e32 v224, v224, v192
	ds_bpermute_b32 v192, v12, v224
	s_waitcnt lgkmcnt(0)
	v_add_f32_e32 v224, v224, v192
	ds_bpermute_b32 v192, v13, v224
	s_waitcnt lgkmcnt(0)
	v_add_f32_e32 v224, v224, v192
	ds_bpermute_b32 v192, v14, v224
	s_waitcnt lgkmcnt(0)
	v_add_f32_e32 v224, v224, v192
	ds_bpermute_b32 v192, v15, v224
	s_waitcnt lgkmcnt(0)
	v_add_f32_e32 v224, v224, v192
	v_fmamk_f32 v224, v224, 0x3a800000, v17
	v_mul_f32_e32 v192, 0x4f800000, v224
	v_cmp_gt_f32_e32 vcc, s17, v224
	s_nop 1
	v_cndmask_b32_e32 v224, v224, v192, vcc
	v_sqrt_f32_e32 v192, v224
	s_nop 0
	v_add_u32_e32 v193, -1, v192
	v_add_u32_e32 v194, 1, v192
	v_fma_f32 v195, -v193, v192, v224
	v_fma_f32 v196, -v194, v192, v224
	v_cmp_ge_f32_e64 s[6:7], 0, v195
	s_nop 1
	v_cndmask_b32_e64 v192, v192, v193, s[6:7]
	v_cmp_lt_f32_e64 s[6:7], 0, v196
	s_nop 1
	v_cndmask_b32_e64 v192, v192, v194, s[6:7]
	v_mul_f32_e32 v193, 0x37800000, v192
	v_cndmask_b32_e32 v192, v192, v193, vcc
	v_cmp_class_f32_e32 vcc, v224, v18
	s_nop 1
	v_cndmask_b32_e32 v224, v192, v224, vcc
	v_div_scale_f32 v192, s[6:7], v224, v224, 1.0
	v_rcp_f32_e32 v194, v192
	v_div_scale_f32 v193, vcc, 1.0, v224, 1.0
	v_fma_f32 v195, -v192, v194, 1.0
	v_fmac_f32_e32 v194, v195, v194
	v_mul_f32_e32 v195, v193, v194
	v_fma_f32 v196, -v192, v195, v193
	v_fmac_f32_e32 v195, v196, v194
	v_fma_f32 v192, -v192, v195, v193
	v_div_fmas_f32 v192, v192, v194, v195
	v_div_fixup_f32 v192, v192, v224, 1.0
	v_pk_mul_f32 v[56:57], v[56:57], v[192:193] op_sel_hi:[1,0]
	v_pk_mul_f32 v[58:59], v[58:59], v[192:193] op_sel_hi:[1,0]
	v_pk_mul_f32 v[56:57], v[88:89], v[56:57]
	v_pk_mul_f32 v[58:59], v[90:91], v[58:59]
	v_cvt_pk_bf16_f32 v56, v56, v57
	v_cvt_pk_bf16_f32 v57, v58, v59
	global_store_dwordx2 v[228:229], v[56:57], off
	v_pk_mul_f32 v[60:61], v[60:61], v[192:193] op_sel_hi:[1,0]
	v_pk_mul_f32 v[62:63], v[62:63], v[192:193] op_sel_hi:[1,0]
	v_pk_mul_f32 v[60:61], v[92:93], v[60:61]
	v_pk_mul_f32 v[62:63], v[94:95], v[62:63]
	v_cvt_pk_bf16_f32 v60, v60, v61
	v_cvt_pk_bf16_f32 v61, v62, v63
	global_store_dwordx2 v[228:229], v[60:61], off offset:256
	v_pk_mul_f32 v[64:65], v[64:65], v[192:193] op_sel_hi:[1,0]
	v_pk_mul_f32 v[66:67], v[66:67], v[192:193] op_sel_hi:[1,0]
	v_pk_mul_f32 v[64:65], v[96:97], v[64:65]
	v_pk_mul_f32 v[66:67], v[98:99], v[66:67]
	v_cvt_pk_bf16_f32 v64, v64, v65
	v_cvt_pk_bf16_f32 v65, v66, v67
	global_store_dwordx2 v[228:229], v[64:65], off offset:512
	v_pk_mul_f32 v[68:69], v[68:69], v[192:193] op_sel_hi:[1,0]
	v_pk_mul_f32 v[70:71], v[70:71], v[192:193] op_sel_hi:[1,0]
	v_pk_mul_f32 v[68:69], v[100:101], v[68:69]
	v_pk_mul_f32 v[70:71], v[102:103], v[70:71]
	v_cvt_pk_bf16_f32 v68, v68, v69
	v_cvt_pk_bf16_f32 v69, v70, v71
	global_store_dwordx2 v[228:229], v[68:69], off offset:768
	v_pk_mul_f32 v[72:73], v[72:73], v[192:193] op_sel_hi:[1,0]
	v_pk_mul_f32 v[74:75], v[74:75], v[192:193] op_sel_hi:[1,0]
	v_pk_mul_f32 v[72:73], v[104:105], v[72:73]
	v_pk_mul_f32 v[74:75], v[106:107], v[74:75]
	v_cvt_pk_bf16_f32 v72, v72, v73
	v_cvt_pk_bf16_f32 v73, v74, v75
	global_store_dwordx2 v[228:229], v[72:73], off offset:1024
	v_pk_mul_f32 v[76:77], v[76:77], v[192:193] op_sel_hi:[1,0]
	v_pk_mul_f32 v[78:79], v[78:79], v[192:193] op_sel_hi:[1,0]
	v_pk_mul_f32 v[76:77], v[108:109], v[76:77]
	v_pk_mul_f32 v[78:79], v[110:111], v[78:79]
	v_cvt_pk_bf16_f32 v76, v76, v77
	v_cvt_pk_bf16_f32 v77, v78, v79
	global_store_dwordx2 v[228:229], v[76:77], off offset:1280
	v_pk_mul_f32 v[80:81], v[80:81], v[192:193] op_sel_hi:[1,0]
	v_pk_mul_f32 v[82:83], v[82:83], v[192:193] op_sel_hi:[1,0]
	v_pk_mul_f32 v[80:81], v[112:113], v[80:81]
	v_pk_mul_f32 v[82:83], v[114:115], v[82:83]
	v_cvt_pk_bf16_f32 v80, v80, v81
	v_cvt_pk_bf16_f32 v81, v82, v83
	global_store_dwordx2 v[228:229], v[80:81], off offset:1536
	v_pk_mul_f32 v[84:85], v[84:85], v[192:193] op_sel_hi:[1,0]
	v_pk_mul_f32 v[86:87], v[86:87], v[192:193] op_sel_hi:[1,0]
	v_pk_mul_f32 v[84:85], v[116:117], v[84:85]
	v_pk_mul_f32 v[86:87], v[118:119], v[86:87]
	v_cvt_pk_bf16_f32 v84, v84, v85
	v_cvt_pk_bf16_f32 v85, v86, v87
	global_store_dwordx2 v[228:229], v[84:85], off offset:1792
	s_cmp_lt_u32 2, s34
	s_cbranch_scc0 .Lp0r_done
; #define GAS __attribute__((address_space(1)))
; __device__ __forceinline__ unsigned pk2(float lo, float hi) { const f32x2_t_ v = {lo, hi}; return __builtin_bit_cast(unsigned, __builtin_convertvector(v, bf16x2_t_)); }
; __device__ __forceinline__ void rms_row2_bf16(const float* xrowA, const float* xrowB, const float* g, bf16* orowA, bf16* orowB, int lane) {
;     const int hl = lane & 31, hw = lane >> 5;
;     const GAS f32x4* xr = (const GAS f32x4*)(hw ? xrowB : xrowA) + hl; const GAS f32x4* gr = (const GAS f32x4*)g + hl;
;     f32x4 v[8]; float s = 0.f;
; #pragma unroll
;     for (int j = 0; j < 8; ++j) { v[j] = xr[32 * j]; s += (v[j].x * v[j].x + v[j].y * v[j].y) + (v[j].z * v[j].z + v[j].w * v[j].w); }
; #pragma unroll
;     for (int o = 1; o < 32; o <<= 1) s += __shfl_xor(s, o);
;     const float rstd = 1.f / sqrtf(s * (1.f / DM) + EPS);
;     GAS v2u* o8 = (GAS v2u*)(hw ? orowB : orowA) + hl;
; #pragma unroll
;     for (int j = 0; j < 8; ++j) { const f32x4 gg = gr[32 * j]; v2u w; w.x = pk2(v[j].x * rstd * gg.x, v[j].y * rstd * gg.y); w.y = pk2(v[j].z * rstd * gg.z, v[j].w * rstd * gg.w); o8[32 * j] = w; }
; }
	s_waitcnt vmcnt(24)
	v_mov_b32_e32 v194, v121
	v_mov_b32_e32 v195, v125
	v_pk_mul_f32 v[196:197], v[130:131], v[130:131]
	v_pk_mul_f32 v[198:199], v[128:129], v[128:129]
	v_pk_mul_f32 v[200:201], v[142:143], v[142:143]
	v_pk_mul_f32 v[202:203], v[140:141], v[140:141]
	v_mov_b32_e32 v206, v123
	v_mov_b32_e32 v207, v127
	v_mov_b32_e32 v192, v120
	v_mov_b32_e32 v193, v124
	v_mov_b32_e32 v204, v122
	v_mov_b32_e32 v205, v126
	v_pk_mov_b32 v[216:217], v[198:199], v[196:197] op_sel:[1,0]
	v_mov_b32_e32 v199, v197
	v_pk_mov_b32 v[196:197], v[202:203], v[200:201] op_sel:[1,0]
	v_mov_b32_e32 v203, v201
	v_pk_mul_f32 v[194:195], v[194:195], v[194:195]
	v_pk_mul_f32 v[200:201], v[206:207], v[206:207]
	v_pk_fma_f32 v[192:193], v[192:193], v[192:193], v[194:195]
	v_pk_fma_f32 v[194:195], v[204:205], v[204:205], v[200:201]
	v_mul_f32_e32 v208, v133, v133
	v_mul_f32_e32 v210, v135, v135
	v_pk_add_f32 v[198:199], v[216:217], v[198:199]
	v_pk_add_f32 v[192:193], v[192:193], v[194:195]
	v_mul_f32_e32 v224, v136, v136
	v_mul_f32_e32 v215, v138, v138
	v_mul_f32_e32 v218, v139, v139
	v_mul_f32_e32 v221, v137, v137
	v_pk_fma_f32 v[206:207], v[132:133], v[132:133], v[208:209] op_sel_hi:[1,1,0]
	v_pk_fma_f32 v[208:209], v[134:135], v[134:135], v[210:211] op_sel_hi:[1,1,0]
	v_pk_add_f32 v[198:199], v[198:199], v[198:199] op_sel:[0,1] op_sel_hi:[1,0]
	v_pk_add_f32 v[192:193], v[192:193], v[192:193] op_sel:[0,1] op_sel_hi:[1,0]
	v_mov_b32_e32 v207, v215
	v_mov_b32_e32 v209, v218
	v_mov_b32_e32 v199, v221
	v_mov_b32_e32 v193, v224
	v_pk_add_f32 v[194:195], v[206:207], v[208:209]
	v_pk_add_f32 v[192:193], v[192:193], v[198:199]
	v_mul_f32_e32 v212, v145, v145
	v_mul_f32_e32 v214, v147, v147
	v_pk_add_f32 v[196:197], v[196:197], v[202:203]
	v_pk_add_f32 v[192:193], v[192:193], v[194:195]
	v_mul_f32_e32 v219, v150, v150
	v_mul_f32_e32 v220, v151, v151
	v_mul_f32_e32 v222, v148, v148
	v_mul_f32_e32 v223, v149, v149
	v_pk_fma_f32 v[210:211], v[144:145], v[144:145], v[212:213] op_sel_hi:[1,1,0]
	v_pk_fma_f32 v[212:213], v[146:147], v[146:147], v[214:215] op_sel_hi:[1,1,0]
	v_pk_add_f32 v[196:197], v[196:197], v[196:197] op_sel:[0,1] op_sel_hi:[1,0]
	v_pk_add_f32 v[192:193], v[192:193], v[192:193] op_sel:[0,1] op_sel_hi:[1,0]
	v_mov_b32_e32 v211, v219
	v_mov_b32_e32 v213, v220
	v_mov_b32_e32 v197, v223
	v_mov_b32_e32 v193, v222
	v_pk_add_f32 v[200:201], v[210:211], v[212:213]
	v_pk_add_f32 v[192:193], v[192:193], v[196:197]
	s_nop 0
	v_pk_add_f32 v[192:193], v[192:193], v[200:201]
	s_nop 0
	v_add_f32_e32 v224, v192, v193
	ds_bpermute_b32 v192, v1, v224
	s_waitcnt lgkmcnt(0)
	v_add_f32_e32 v224, v224, v192
	ds_bpermute_b32 v192, v12, v224
	s_waitcnt lgkmcnt(0)
	v_add_f32_e32 v224, v224, v192
	ds_bpermute_b32 v192, v13, v224
	s_waitcnt lgkmcnt(0)
	v_add_f32_e32 v224, v224, v192
	ds_bpermute_b32 v192, v14, v224
	s_waitcnt lgkmcnt(0)
	v_add_f32_e32 v224, v224, v192
	ds_bpermute_b32 v192, v15, v224
	s_waitcnt lgkmcnt(0)
	v_add_f32_e32 v224, v224, v192
	v_fmamk_f32 v224, v224, 0x3a800000, v17
	v_mul_f32_e32 v192, 0x4f800000, v224
	v_cmp_gt_f32_e32 vcc, s17, v224
	s_nop 1
	v_cndmask_b32_e32 v224, v224, v192, vcc
	v_sqrt_f32_e32 v192, v224
	s_nop 0
	v_add_u32_e32 v193, -1, v192
	v_add_u32_e32 v194, 1, v192
	v_fma_f32 v195, -v193, v192, v224
	v_fma_f32 v196, -v194, v192, v224
	v_cmp_ge_f32_e64 s[6:7], 0, v195
	s_nop 1
	v_cndmask_b32_e64 v192, v192, v193, s[6:7]
	v_cmp_lt_f32_e64 s[6:7], 0, v196
	s_nop 1
	v_cndmask_b32_e64 v192, v192, v194, s[6:7]
	v_mul_f32_e32 v193, 0x37800000, v192
	v_cndmask_b32_e32 v192, v192, v193, vcc
	v_cmp_class_f32_e32 vcc, v224, v18
	s_nop 1
	v_cndmask_b32_e32 v224, v192, v224, vcc
	v_div_scale_f32 v192, s[6:7], v224, v224, 1.0
	v_rcp_f32_e32 v194, v192
	v_div_scale_f32 v193, vcc, 1.0, v224, 1.0
	v_fma_f32 v195, -v192, v194, 1.0
	v_fmac_f32_e32 v194, v195, v194
	v_mul_f32_e32 v195, v193, v194
	v_fma_f32 v196, -v192, v195, v193
	v_fmac_f32_e32 v195, v196, v194
	v_fma_f32 v192, -v192, v195, v193
	v_div_fmas_f32 v192, v192, v194, v195
	v_div_fixup_f32 v192, v192, v224, 1.0
	v_pk_mul_f32 v[120:121], v[120:121], v[192:193] op_sel_hi:[1,0]
	v_pk_mul_f32 v[122:123], v[122:123], v[192:193] op_sel_hi:[1,0]
	v_pk_mul_f32 v[120:121], v[88:89], v[120:121]
	v_pk_mul_f32 v[122:123], v[90:91], v[122:123]
	v_cvt_pk_bf16_f32 v120, v120, v121
	v_cvt_pk_bf16_f32 v121, v122, v123
	global_store_dwordx2 v[230:231], v[120:121], off
	v_pk_mul_f32 v[124:125], v[124:125], v[192:193] op_sel_hi:[1,0]
	v_pk_mul_f32 v[126:127], v[126:127], v[192:193] op_sel_hi:[1,0]
	v_pk_mul_f32 v[124:125], v[92:93], v[124:125]
	v_pk_mul_f32 v[126:127], v[94:95], v[126:127]
	v_cvt_pk_bf16_f32 v124, v124, v125
	v_cvt_pk_bf16_f32 v125, v126, v127
	global_store_dwordx2 v[230:231], v[124:125], off offset:256
	v_pk_mul_f32 v[128:129], v[128:129], v[192:193] op_sel_hi:[1,0]
	v_pk_mul_f32 v[130:131], v[130:131], v[192:193] op_sel_hi:[1,0]
	v_pk_mul_f32 v[128:129], v[96:97], v[128:129]
	v_pk_mul_f32 v[130:131], v[98:99], v[130:131]
	v_cvt_pk_bf16_f32 v128, v128, v129
	v_cvt_pk_bf16_f32 v129, v130, v131
	global_store_dwordx2 v[230:231], v[128:129], off offset:512
	v_pk_mul_f32 v[132:133], v[132:133], v[192:193] op_sel_hi:[1,0]
	v_pk_mul_f32 v[134:135], v[134:135], v[192:193] op_sel_hi:[1,0]
	v_pk_mul_f32 v[132:133], v[100:101], v[132:133]
	v_pk_mul_f32 v[134:135], v[102:103], v[134:135]
	v_cvt_pk_bf16_f32 v132, v132, v133
	v_cvt_pk_bf16_f32 v133, v134, v135
	global_store_dwordx2 v[230:231], v[132:133], off offset:768
	v_pk_mul_f32 v[136:137], v[136:137], v[192:193] op_sel_hi:[1,0]
	v_pk_mul_f32 v[138:139], v[138:139], v[192:193] op_sel_hi:[1,0]
	v_pk_mul_f32 v[136:137], v[104:105], v[136:137]
	v_pk_mul_f32 v[138:139], v[106:107], v[138:139]
	v_cvt_pk_bf16_f32 v136, v136, v137
	v_cvt_pk_bf16_f32 v137, v138, v139
	global_store_dwordx2 v[230:231], v[136:137], off offset:1024
	v_pk_mul_f32 v[140:141], v[140:141], v[192:193] op_sel_hi:[1,0]
	v_pk_mul_f32 v[142:143], v[142:143], v[192:193] op_sel_hi:[1,0]
	v_pk_mul_f32 v[140:141], v[108:109], v[140:141]
	v_pk_mul_f32 v[142:143], v[110:111], v[142:143]
	v_cvt_pk_bf16_f32 v140, v140, v141
	v_cvt_pk_bf16_f32 v141, v142, v143
	global_store_dwordx2 v[230:231], v[140:141], off offset:1280
	v_pk_mul_f32 v[144:145], v[144:145], v[192:193] op_sel_hi:[1,0]
	v_pk_mul_f32 v[146:147], v[146:147], v[192:193] op_sel_hi:[1,0]
	v_pk_mul_f32 v[144:145], v[112:113], v[144:145]
	v_pk_mul_f32 v[146:147], v[114:115], v[146:147]
	v_cvt_pk_bf16_f32 v144, v144, v145
	v_cvt_pk_bf16_f32 v145, v146, v147
	global_store_dwordx2 v[230:231], v[144:145], off offset:1536
	v_pk_mul_f32 v[148:149], v[148:149], v[192:193] op_sel_hi:[1,0]
	v_pk_mul_f32 v[150:151], v[150:151], v[192:193] op_sel_hi:[1,0]
	v_pk_mul_f32 v[148:149], v[116:117], v[148:149]
	v_pk_mul_f32 v[150:151], v[118:119], v[150:151]
	v_cvt_pk_bf16_f32 v148, v148, v149
	v_cvt_pk_bf16_f32 v149, v150, v151
	global_store_dwordx2 v[230:231], v[148:149], off offset:1792
	s_cmp_lt_u32 3, s34
	s_cbranch_scc0 .Lp0r_done
; #define GAS __attribute__((address_space(1)))
; __device__ __forceinline__ unsigned pk2(float lo, float hi) { const f32x2_t_ v = {lo, hi}; return __builtin_bit_cast(unsigned, __builtin_convertvector(v, bf16x2_t_)); }
; __device__ __forceinline__ void rms_row2_bf16(const float* xrowA, const float* xrowB, const float* g, bf16* orowA, bf16* orowB, int lane) {
;     const int hl = lane & 31, hw = lane >> 5;
;     const GAS f32x4* xr = (const GAS f32x4*)(hw ? xrowB : xrowA) + hl; const GAS f32x4* gr = (const GAS f32x4*)g + hl;
;     f32x4 v[8]; float s = 0.f;
; #pragma unroll
;     for (int j = 0; j < 8; ++j) { v[j] = xr[32 * j]; s += (v[j].x * v[j].x + v[j].y * v[j].y) + (v[j].z * v[j].z + v[j].w * v[j].w); }
; #pragma unroll
;     for (int o = 1; o < 32; o <<= 1) s += __shfl_xor(s, o);
;     const float rstd = 1.f / sqrtf(s * (1.f / DM) + EPS);
;     GAS v2u* o8 = (GAS v2u*)(hw ? orowB : orowA) + hl;
; #pragma unroll
;     for (int j = 0; j < 8; ++j) { const f32x4 gg = gr[32 * j]; v2u w; w.x = pk2(v[j].x * rstd * gg.x, v[j].y * rstd * gg.y); w.y = pk2(v[j].z * rstd * gg.z, v[j].w * rstd * gg.w); o8[32 * j] = w; }
; }
; __global__ void __launch_bounds__(NWAVES * 64, 2) mk_fwd(Args args) {
;     ...
;           for (int m = 2 * GW_; m < T; m += 2 * NGW) { const float* ra = m < TP ? xp + (size_t)m * DM : xs + (size_t)(m - TP) * DM;
;               rms_row2_bf16(ra, ra + DM, g1, XN + (size_t)m * DM, XN + (size_t)(m + 1) * DM, F.lane); } }
	s_waitcnt vmcnt(24)
	v_mov_b32_e32 v194, v153
	v_mov_b32_e32 v195, v157
	v_pk_mul_f32 v[196:197], v[162:163], v[162:163]
	v_pk_mul_f32 v[198:199], v[160:161], v[160:161]
	v_pk_mul_f32 v[200:201], v[174:175], v[174:175]
	v_pk_mul_f32 v[202:203], v[172:173], v[172:173]
	v_mov_b32_e32 v206, v155
	v_mov_b32_e32 v207, v159
	v_mov_b32_e32 v192, v152
	v_mov_b32_e32 v193, v156
	v_mov_b32_e32 v204, v154
	v_mov_b32_e32 v205, v158
	v_pk_mov_b32 v[216:217], v[198:199], v[196:197] op_sel:[1,0]
	v_mov_b32_e32 v199, v197
	v_pk_mov_b32 v[196:197], v[202:203], v[200:201] op_sel:[1,0]
	v_mov_b32_e32 v203, v201
	v_pk_mul_f32 v[194:195], v[194:195], v[194:195]
	v_pk_mul_f32 v[200:201], v[206:207], v[206:207]
	v_pk_fma_f32 v[192:193], v[192:193], v[192:193], v[194:195]
	v_pk_fma_f32 v[194:195], v[204:205], v[204:205], v[200:201]
	v_mul_f32_e32 v208, v165, v165
	v_mul_f32_e32 v210, v167, v167
	v_pk_add_f32 v[198:199], v[216:217], v[198:199]
	v_pk_add_f32 v[192:193], v[192:193], v[194:195]
	v_mul_f32_e32 v224, v168, v168
	v_mul_f32_e32 v215, v170, v170
	v_mul_f32_e32 v218, v171, v171
	v_mul_f32_e32 v221, v169, v169
	v_pk_fma_f32 v[206:207], v[164:165], v[164:165], v[208:209] op_sel_hi:[1,1,0]
	v_pk_fma_f32 v[208:209], v[166:167], v[166:167], v[210:211] op_sel_hi:[1,1,0]
	v_pk_add_f32 v[198:199], v[198:199], v[198:199] op_sel:[0,1] op_sel_hi:[1,0]
	v_pk_add_f32 v[192:193], v[192:193], v[192:193] op_sel:[0,1] op_sel_hi:[1,0]
	v_mov_b32_e32 v207, v215
	v_mov_b32_e32 v209, v218
	v_mov_b32_e32 v199, v221
	v_mov_b32_e32 v193, v224
	v_pk_add_f32 v[194:195], v[206:207], v[208:209]
	v_pk_add_f32 v[192:193], v[192:193], v[198:199]
	v_mul_f32_e32 v212, v177, v177
	v_mul_f32_e32 v214, v179, v179
	v_pk_add_f32 v[196:197], v[196:197], v[202:203]
	v_pk_add_f32 v[192:193], v[192:193], v[194:195]
	v_mul_f32_e32 v219, v182, v182
	v_mul_f32_e32 v220, v183, v183
	v_mul_f32_e32 v222, v180, v180
	v_mul_f32_e32 v223, v181, v181
	v_pk_fma_f32 v[210:211], v[176:177], v[176:177], v[212:213] op_sel_hi:[1,1,0]
	v_pk_fma_f32 v[212:213], v[178:179], v[178:179], v[214:215] op_sel_hi:[1,1,0]
	v_pk_add_f32 v[196:197], v[196:197], v[196:197] op_sel:[0,1] op_sel_hi:[1,0]
	v_pk_add_f32 v[192:193], v[192:193], v[192:193] op_sel:[0,1] op_sel_hi:[1,0]
	v_mov_b32_e32 v211, v219
	v_mov_b32_e32 v213, v220
	v_mov_b32_e32 v197, v223
	v_mov_b32_e32 v193, v222
	v_pk_add_f32 v[200:201], v[210:211], v[212:213]
	v_pk_add_f32 v[192:193], v[192:193], v[196:197]
	s_nop 0
	v_pk_add_f32 v[192:193], v[192:193], v[200:201]
	s_nop 0
	v_add_f32_e32 v224, v192, v193
	ds_bpermute_b32 v192, v1, v224
	s_waitcnt lgkmcnt(0)
	v_add_f32_e32 v224, v224, v192
	ds_bpermute_b32 v192, v12, v224
	s_waitcnt lgkmcnt(0)
	v_add_f32_e32 v224, v224, v192
	ds_bpermute_b32 v192, v13, v224
	s_waitcnt lgkmcnt(0)
	v_add_f32_e32 v224, v224, v192
	ds_bpermute_b32 v192, v14, v224
	s_waitcnt lgkmcnt(0)
	v_add_f32_e32 v224, v224, v192
	ds_bpermute_b32 v192, v15, v224
	s_waitcnt lgkmcnt(0)
	v_add_f32_e32 v224, v224, v192
	v_fmamk_f32 v224, v224, 0x3a800000, v17
	v_mul_f32_e32 v192, 0x4f800000, v224
	v_cmp_gt_f32_e32 vcc, s17, v224
	s_nop 1
	v_cndmask_b32_e32 v224, v224, v192, vcc
	v_sqrt_f32_e32 v192, v224
	s_nop 0
	v_add_u32_e32 v193, -1, v192
	v_add_u32_e32 v194, 1, v192
	v_fma_f32 v195, -v193, v192, v224
	v_fma_f32 v196, -v194, v192, v224
	v_cmp_ge_f32_e64 s[6:7], 0, v195
	s_nop 1
	v_cndmask_b32_e64 v192, v192, v193, s[6:7]
	v_cmp_lt_f32_e64 s[6:7], 0, v196
	s_nop 1
	v_cndmask_b32_e64 v192, v192, v194, s[6:7]
	v_mul_f32_e32 v193, 0x37800000, v192
	v_cndmask_b32_e32 v192, v192, v193, vcc
	v_cmp_class_f32_e32 vcc, v224, v18
	s_nop 1
	v_cndmask_b32_e32 v224, v192, v224, vcc
	v_div_scale_f32 v192, s[6:7], v224, v224, 1.0
	v_rcp_f32_e32 v194, v192
	v_div_scale_f32 v193, vcc, 1.0, v224, 1.0
	v_fma_f32 v195, -v192, v194, 1.0
	v_fmac_f32_e32 v194, v195, v194
	v_mul_f32_e32 v195, v193, v194
	v_fma_f32 v196, -v192, v195, v193
	v_fmac_f32_e32 v195, v196, v194
	v_fma_f32 v192, -v192, v195, v193
	v_div_fmas_f32 v192, v192, v194, v195
	v_div_fixup_f32 v192, v192, v224, 1.0
	v_pk_mul_f32 v[152:153], v[152:153], v[192:193] op_sel_hi:[1,0]
	v_pk_mul_f32 v[154:155], v[154:155], v[192:193] op_sel_hi:[1,0]
	v_pk_mul_f32 v[152:153], v[88:89], v[152:153]
	v_pk_mul_f32 v[154:155], v[90:91], v[154:155]
	v_cvt_pk_bf16_f32 v152, v152, v153
	v_cvt_pk_bf16_f32 v153, v154, v155
	global_store_dwordx2 v[232:233], v[152:153], off
	v_pk_mul_f32 v[156:157], v[156:157], v[192:193] op_sel_hi:[1,0]
	v_pk_mul_f32 v[158:159], v[158:159], v[192:193] op_sel_hi:[1,0]
	v_pk_mul_f32 v[156:157], v[92:93], v[156:157]
	v_pk_mul_f32 v[158:159], v[94:95], v[158:159]
	v_cvt_pk_bf16_f32 v156, v156, v157
	v_cvt_pk_bf16_f32 v157, v158, v159
	global_store_dwordx2 v[232:233], v[156:157], off offset:256
	v_pk_mul_f32 v[160:161], v[160:161], v[192:193] op_sel_hi:[1,0]
	v_pk_mul_f32 v[162:163], v[162:163], v[192:193] op_sel_hi:[1,0]
	v_pk_mul_f32 v[160:161], v[96:97], v[160:161]
	v_pk_mul_f32 v[162:163], v[98:99], v[162:163]
	v_cvt_pk_bf16_f32 v160, v160, v161
	v_cvt_pk_bf16_f32 v161, v162, v163
	global_store_dwordx2 v[232:233], v[160:161], off offset:512
	v_pk_mul_f32 v[164:165], v[164:165], v[192:193] op_sel_hi:[1,0]
	v_pk_mul_f32 v[166:167], v[166:167], v[192:193] op_sel_hi:[1,0]
	v_pk_mul_f32 v[164:165], v[100:101], v[164:165]
	v_pk_mul_f32 v[166:167], v[102:103], v[166:167]
	v_cvt_pk_bf16_f32 v164, v164, v165
	v_cvt_pk_bf16_f32 v165, v166, v167
	global_store_dwordx2 v[232:233], v[164:165], off offset:768
	v_pk_mul_f32 v[168:169], v[168:169], v[192:193] op_sel_hi:[1,0]
	v_pk_mul_f32 v[170:171], v[170:171], v[192:193] op_sel_hi:[1,0]
	v_pk_mul_f32 v[168:169], v[104:105], v[168:169]
	v_pk_mul_f32 v[170:171], v[106:107], v[170:171]
	v_cvt_pk_bf16_f32 v168, v168, v169
	v_cvt_pk_bf16_f32 v169, v170, v171
	global_store_dwordx2 v[232:233], v[168:169], off offset:1024
	v_pk_mul_f32 v[172:173], v[172:173], v[192:193] op_sel_hi:[1,0]
	v_pk_mul_f32 v[174:175], v[174:175], v[192:193] op_sel_hi:[1,0]
	v_pk_mul_f32 v[172:173], v[108:109], v[172:173]
	v_pk_mul_f32 v[174:175], v[110:111], v[174:175]
	v_cvt_pk_bf16_f32 v172, v172, v173
	v_cvt_pk_bf16_f32 v173, v174, v175
	global_store_dwordx2 v[232:233], v[172:173], off offset:1280
	v_pk_mul_f32 v[176:177], v[176:177], v[192:193] op_sel_hi:[1,0]
	v_pk_mul_f32 v[178:179], v[178:179], v[192:193] op_sel_hi:[1,0]
	v_pk_mul_f32 v[176:177], v[112:113], v[176:177]
	v_pk_mul_f32 v[178:179], v[114:115], v[178:179]
	v_cvt_pk_bf16_f32 v176, v176, v177
	v_cvt_pk_bf16_f32 v177, v178, v179
	global_store_dwordx2 v[232:233], v[176:177], off offset:1536
	v_pk_mul_f32 v[180:181], v[180:181], v[192:193] op_sel_hi:[1,0]
	v_pk_mul_f32 v[182:183], v[182:183], v[192:193] op_sel_hi:[1,0]
	v_pk_mul_f32 v[180:181], v[116:117], v[180:181]
	v_pk_mul_f32 v[182:183], v[118:119], v[182:183]
	v_cvt_pk_bf16_f32 v180, v180, v181
	v_cvt_pk_bf16_f32 v181, v182, v183
	global_store_dwordx2 v[232:233], v[180:181], off offset:1792
.Lp0r_done:
	s_cmpk_gt_i32 s19, 0x43ff
	s_cbranch_scc0 .Lp0r_outer
